# static s_setprio 1 for the younger co-resident blocks (blockIdx >= 256)
# speedup vs baseline: 1.0086x; 1.0086x over previous
; #define LAS __attribute__((address_space(3)))
; __global__ void __launch_bounds__(NTHR, 2) fwd_megakernel(Params p0) {
;   __shared__ __attribute__((aligned(16))) char lds[65536];
;   cg::grid_group grid = cg::this_grid();
;   __shared__ uint4 xb_words;
;   if (threadIdx.x == 0) xb_words = make_uint4(0u, 0u, 0u, 0u);
;   __syncthreads();
;   const XcdBarrier xb = xcd_barrier_post((unsigned*)(p0.ws + OFF_BAR), (volatile LAS unsigned*)&xb_words);
_Z14fwd_megakernel6Params:
	v_mov_b32_e32 v245, 0
	s_add_u32 s6, s0, 0x100
	v_and_b32_e32 v178, 0x3ff, v0
	s_mov_b32 s96, s2
	v_writelane_b32 v244, s0, 0
	s_addc_u32 s7, s1, 0
	s_cmpk_lt_u32 s2, 0x100
	s_cbranch_scc1 .Lprio_skip
	s_setprio 1
.Lprio_skip:
	v_cmp_ne_u32_e64 s[72:73], 0, v178
	v_cmp_eq_u32_e64 s[90:91], 0, v178
	v_writelane_b32 v244, s1, 1
	s_and_saveexec_b64 s[2:3], s[90:91]
	s_cbranch_execz .LBB0_2
	v_mov_b32_e32 v2, 0
	v_mov_b32_e32 v3, v2
	v_mov_b32_e32 v4, v2
	v_mov_b32_e32 v5, v2
	v_mov_b32_e32 v1, 0x10000
	ds_write_b128 v1, v[2:5]
